# v5 plus queue order: big conv items ahead of the last 256 diff-attn units
# speedup vs baseline: 1.0822x; 1.0008x over previous
.LBB0_691:
	s_or_b64 exec, exec, s[4:5]
	s_waitcnt lgkmcnt(0)
	s_barrier
	s_waitcnt vmcnt(0)
	ds_read_b32 v2, v207
	s_movk_i32 s0, 0xdff
	s_mov_b64 s[4:5], -1
	s_waitcnt lgkmcnt(0)
	s_barrier
	v_cmp_lt_i32_e32 vcc, s0, v2
	v_readfirstlane_b32 s58, v2
	s_cbranch_vccnz .LBB0_686
	s_cmpk_lt_u32 s58, 2368
	s_cbranch_scc1 .Lq0_p0
	s_cmpk_ge_u32 s58, 3072
	s_cbranch_scc1 .Lq0_p0
	s_cmpk_ge_u32 s58, 2816
	s_cbranch_scc1 .Lq0_pa
	s_addk_i32 s58, 256
	s_branch .Lq0_p0
.Lq0_pa:
	s_addk_i32 s58, -448
.Lq0_p0:
	s_cmpk_lt_u32 s58, 576
	s_cbranch_scc1 .Lq0_done
	s_cmpk_ge_u32 s58, 1344
	s_cbranch_scc1 .Lq0_done
	s_sub_u32 s0, s58, 576
	s_mul_hi_u32 s29, s0, 0xaaaaaaab
	s_lshr_b32 s29, s29, 1
	s_mul_i32 vcc_lo, s29, 3
	s_sub_u32 s0, s0, vcc_lo
	s_cmp_eq_u32 s0, 0
	s_cbranch_scc1 .Lq0_r1s
	s_lshl_b32 s29, s29, 1
	s_add_u32 s58, s29, s0
	s_addk_i32 s58, 575
	s_branch .Lq0_done
